# plus scan conv: inputs and weights of all four taps loaded up front (one wait) instead of four serialized load rounds
# speedup vs baseline: 1.0020x; 1.0020x over previous
.LBB0_892:
	s_or_b64 exec, exec, s[30:31]
	s_lshl_b32 s44, s47, 6
	s_lshl_b32 s25, s24, 3
	s_and_b32 s25, s25, 0x7fffff00
	s_and_b32 s34, s44, 0x7ffff000
	s_and_b64 s[30:31], s[28:29], exec
	s_cselect_b32 s30, 0x100, s38
	s_cselect_b32 s37, s25, s34
	s_add_i32 s36, s37, s30
	s_barrier
	s_load_dwordx2 s[34:35], s[22:23], 0xa0
	s_add_u32 s30, s26, 0xaa08000
	v_lshlrev_b32_e32 v0, 4, v72
	s_addc_u32 s31, s27, 0
	v_and_b32_e32 v1, 48, v0
	s_lshl_b32 s25, s46, 6
	v_or_b32_e32 v2, s25, v1
	v_lshlrev_b32_e32 v20, 2, v2
	s_waitcnt lgkmcnt(0)
	global_load_dwordx4 v[8:11], v20, s[34:35] offset:48
	global_load_dwordx4 v[4:7], v20, s[34:35] offset:32
	global_load_dwordx4 v[16:19], v20, s[34:35] offset:16
	global_load_dwordx4 v[12:15], v20, s[34:35]
	v_lshrrev_b32_e32 v73, 2, v72
	v_or_b32_e32 v0, s44, v73
	v_add_u32_e32 v21, -2, v0
	v_lshlrev_b32_e32 v2, 1, v2
	v_cmp_le_i32_e32 vcc, s37, v21
	v_cmp_gt_i32_e64 s[44:45], s36, v21
	v_lshl_add_u64 v[22:23], s[30:31], 0, v[2:3]
	s_load_dwordx2 s[44:45], s[22:23], 0x98
	v_mov_b32_e32 v74, 0
	v_mov_b32_e32 v75, 0
	v_mov_b32_e32 v76, 0
	v_mov_b32_e32 v77, 0
	v_mov_b32_e32 v78, 0
	v_mov_b32_e32 v79, 0
	v_mov_b32_e32 v80, 0
	v_mov_b32_e32 v81, 0
	v_mov_b32_e32 v82, 0
	v_mov_b32_e32 v83, 0
	v_mov_b32_e32 v84, 0
	v_mov_b32_e32 v85, 0
	v_mov_b32_e32 v86, 0
	v_mov_b32_e32 v87, 0
	v_mov_b32_e32 v88, 0
	v_mov_b32_e32 v89, 0
	v_mov_b32_e32 v90, 0
	v_mov_b32_e32 v91, 0
	v_mov_b32_e32 v92, 0
	v_mov_b32_e32 v93, 0
	v_mov_b32_e32 v94, 0
	v_mov_b32_e32 v95, 0
	v_mov_b32_e32 v96, 0
	v_mov_b32_e32 v97, 0
	v_mov_b32_e32 v98, 0
	v_mov_b32_e32 v99, 0
	v_mov_b32_e32 v100, 0
	v_mov_b32_e32 v101, 0
	v_mov_b32_e32 v102, 0
	v_mov_b32_e32 v103, 0
	v_mov_b32_e32 v104, 0
	v_mov_b32_e32 v105, 0
	v_add_u32_e32 v108, 0x1000, v20
	v_add_u32_e32 v109, -2, v0
	v_cmp_le_i32_e32 vcc, s37, v109
	v_cmp_gt_i32_e64 s[34:35], s36, v109
	s_and_b64 vcc, vcc, s[34:35]
	s_and_saveexec_b64 s[34:35], vcc
	s_cbranch_execz .Lcvb_0
	v_mad_u64_u32 v[106:107], vcc, v109, s97, v[22:23]
	global_load_dwordx4 v[74:77], v[106:107], off
	global_load_dwordx4 v[78:81], v[106:107], off offset:16
.Lcvb_0:
	s_or_b64 exec, exec, s[34:35]
	v_add_u32_e32 v109, -1, v0
	v_cmp_le_i32_e32 vcc, s37, v109
	v_cmp_gt_i32_e64 s[34:35], s36, v109
	s_and_b64 vcc, vcc, s[34:35]
	s_and_saveexec_b64 s[34:35], vcc
	s_cbranch_execz .Lcvb_1
	v_mad_u64_u32 v[106:107], vcc, v109, s97, v[22:23]
	global_load_dwordx4 v[82:85], v[106:107], off
	global_load_dwordx4 v[86:89], v[106:107], off offset:16
.Lcvb_1:
	s_or_b64 exec, exec, s[34:35]
	v_mov_b32_e32 v109, v0
	v_cmp_le_i32_e32 vcc, s37, v109
	v_cmp_gt_i32_e64 s[34:35], s36, v109
	s_and_b64 vcc, vcc, s[34:35]
	s_and_saveexec_b64 s[34:35], vcc
	s_cbranch_execz .Lcvb_2
	v_mad_u64_u32 v[106:107], vcc, v109, s97, v[22:23]
	global_load_dwordx4 v[90:93], v[106:107], off
	global_load_dwordx4 v[94:97], v[106:107], off offset:16
.Lcvb_2:
	s_or_b64 exec, exec, s[34:35]
	v_add_u32_e32 v109, 1, v0
	v_cmp_le_i32_e32 vcc, s37, v109
	v_cmp_gt_i32_e64 s[34:35], s36, v109
	s_and_b64 vcc, vcc, s[34:35]
	s_and_saveexec_b64 s[34:35], vcc
	s_cbranch_execz .Lcvb_3
	v_mad_u64_u32 v[106:107], vcc, v109, s97, v[22:23]
	global_load_dwordx4 v[98:101], v[106:107], off
	global_load_dwordx4 v[102:105], v[106:107], off offset:16
.Lcvb_3:
	s_or_b64 exec, exec, s[34:35]
	s_waitcnt lgkmcnt(0)
	global_load_dwordx4 v[110:113], v20, s[44:45]
	global_load_dwordx4 v[114:117], v20, s[44:45] offset:16
	global_load_dwordx4 v[118:121], v20, s[44:45] offset:32
	global_load_dwordx4 v[122:125], v20, s[44:45] offset:48
	global_load_dwordx4 v[126:129], v20, s[44:45] offset:2048
	global_load_dwordx4 v[130:133], v20, s[44:45] offset:2064
	global_load_dwordx4 v[134:137], v20, s[44:45] offset:2080
	global_load_dwordx4 v[138:141], v20, s[44:45] offset:2096
	global_load_dwordx4 v[142:145], v108, s[44:45]
	global_load_dwordx4 v[146:149], v108, s[44:45] offset:16
	global_load_dwordx4 v[150:153], v108, s[44:45] offset:32
	global_load_dwordx4 v[154:157], v108, s[44:45] offset:48
	global_load_dwordx4 v[158:161], v108, s[44:45] offset:2048
	global_load_dwordx4 v[162:165], v108, s[44:45] offset:2064
	global_load_dwordx4 v[166:169], v108, s[44:45] offset:2080
	global_load_dwordx4 v[170:173], v108, s[44:45] offset:2096
	s_waitcnt vmcnt(0)
	v_cvt_f32_f16_e32 v26, v74
	v_cvt_f32_f16_sdwa v27, v74 dst_sel:DWORD dst_unused:UNUSED_PAD src0_sel:WORD_1
	v_cvt_f32_f16_e32 v28, v75
	v_cvt_f32_f16_sdwa v29, v75 dst_sel:DWORD dst_unused:UNUSED_PAD src0_sel:WORD_1
	v_cvt_f32_f16_e32 v30, v76
	v_cvt_f32_f16_sdwa v31, v76 dst_sel:DWORD dst_unused:UNUSED_PAD src0_sel:WORD_1
	v_cvt_f32_f16_e32 v32, v77
	v_cvt_f32_f16_sdwa v33, v77 dst_sel:DWORD dst_unused:UNUSED_PAD src0_sel:WORD_1
	v_cvt_f32_f16_e32 v34, v78
	v_cvt_f32_f16_sdwa v35, v78 dst_sel:DWORD dst_unused:UNUSED_PAD src0_sel:WORD_1
	v_cvt_f32_f16_e32 v36, v79
	v_cvt_f32_f16_sdwa v37, v79 dst_sel:DWORD dst_unused:UNUSED_PAD src0_sel:WORD_1
	v_cvt_f32_f16_e32 v38, v80
	v_cvt_f32_f16_sdwa v39, v80 dst_sel:DWORD dst_unused:UNUSED_PAD src0_sel:WORD_1
	v_cvt_f32_f16_e32 v40, v81
	v_cvt_f32_f16_sdwa v41, v81 dst_sel:DWORD dst_unused:UNUSED_PAD src0_sel:WORD_1
	v_pk_fma_f32 v[12:13], v[110:111], v[26:27], v[12:13]
	v_pk_fma_f32 v[14:15], v[112:113], v[28:29], v[14:15]
	v_pk_fma_f32 v[16:17], v[114:115], v[30:31], v[16:17]
	v_pk_fma_f32 v[18:19], v[116:117], v[32:33], v[18:19]
	v_pk_fma_f32 v[4:5], v[118:119], v[34:35], v[4:5]
	v_pk_fma_f32 v[6:7], v[120:121], v[36:37], v[6:7]
	v_pk_fma_f32 v[8:9], v[122:123], v[38:39], v[8:9]
	v_pk_fma_f32 v[10:11], v[124:125], v[40:41], v[10:11]
	v_cvt_f32_f16_e32 v26, v82
	v_cvt_f32_f16_sdwa v27, v82 dst_sel:DWORD dst_unused:UNUSED_PAD src0_sel:WORD_1
	v_cvt_f32_f16_e32 v28, v83
	v_cvt_f32_f16_sdwa v29, v83 dst_sel:DWORD dst_unused:UNUSED_PAD src0_sel:WORD_1
	v_cvt_f32_f16_e32 v30, v84
	v_cvt_f32_f16_sdwa v31, v84 dst_sel:DWORD dst_unused:UNUSED_PAD src0_sel:WORD_1
	v_cvt_f32_f16_e32 v32, v85
	v_cvt_f32_f16_sdwa v33, v85 dst_sel:DWORD dst_unused:UNUSED_PAD src0_sel:WORD_1
	v_cvt_f32_f16_e32 v34, v86
	v_cvt_f32_f16_sdwa v35, v86 dst_sel:DWORD dst_unused:UNUSED_PAD src0_sel:WORD_1
	v_cvt_f32_f16_e32 v36, v87
	v_cvt_f32_f16_sdwa v37, v87 dst_sel:DWORD dst_unused:UNUSED_PAD src0_sel:WORD_1
	v_cvt_f32_f16_e32 v38, v88
	v_cvt_f32_f16_sdwa v39, v88 dst_sel:DWORD dst_unused:UNUSED_PAD src0_sel:WORD_1
	v_cvt_f32_f16_e32 v40, v89
	v_cvt_f32_f16_sdwa v41, v89 dst_sel:DWORD dst_unused:UNUSED_PAD src0_sel:WORD_1
	v_pk_fma_f32 v[12:13], v[126:127], v[26:27], v[12:13]
	v_pk_fma_f32 v[14:15], v[128:129], v[28:29], v[14:15]
	v_pk_fma_f32 v[16:17], v[130:131], v[30:31], v[16:17]
	v_pk_fma_f32 v[18:19], v[132:133], v[32:33], v[18:19]
	v_pk_fma_f32 v[4:5], v[134:135], v[34:35], v[4:5]
	v_pk_fma_f32 v[6:7], v[136:137], v[36:37], v[6:7]
	v_pk_fma_f32 v[8:9], v[138:139], v[38:39], v[8:9]
	v_pk_fma_f32 v[10:11], v[140:141], v[40:41], v[10:11]
	v_cvt_f32_f16_e32 v26, v90
	v_cvt_f32_f16_sdwa v27, v90 dst_sel:DWORD dst_unused:UNUSED_PAD src0_sel:WORD_1
	v_cvt_f32_f16_e32 v28, v91
	v_cvt_f32_f16_sdwa v29, v91 dst_sel:DWORD dst_unused:UNUSED_PAD src0_sel:WORD_1
	v_cvt_f32_f16_e32 v30, v92
	v_cvt_f32_f16_sdwa v31, v92 dst_sel:DWORD dst_unused:UNUSED_PAD src0_sel:WORD_1
	v_cvt_f32_f16_e32 v32, v93
	v_cvt_f32_f16_sdwa v33, v93 dst_sel:DWORD dst_unused:UNUSED_PAD src0_sel:WORD_1
	v_cvt_f32_f16_e32 v34, v94
	v_cvt_f32_f16_sdwa v35, v94 dst_sel:DWORD dst_unused:UNUSED_PAD src0_sel:WORD_1
	v_cvt_f32_f16_e32 v36, v95
	v_cvt_f32_f16_sdwa v37, v95 dst_sel:DWORD dst_unused:UNUSED_PAD src0_sel:WORD_1
	v_cvt_f32_f16_e32 v38, v96
	v_cvt_f32_f16_sdwa v39, v96 dst_sel:DWORD dst_unused:UNUSED_PAD src0_sel:WORD_1
	v_cvt_f32_f16_e32 v40, v97
	v_cvt_f32_f16_sdwa v41, v97 dst_sel:DWORD dst_unused:UNUSED_PAD src0_sel:WORD_1
	v_pk_fma_f32 v[12:13], v[142:143], v[26:27], v[12:13]
	v_pk_fma_f32 v[14:15], v[144:145], v[28:29], v[14:15]
	v_pk_fma_f32 v[16:17], v[146:147], v[30:31], v[16:17]
	v_pk_fma_f32 v[18:19], v[148:149], v[32:33], v[18:19]
	v_pk_fma_f32 v[4:5], v[150:151], v[34:35], v[4:5]
	v_pk_fma_f32 v[6:7], v[152:153], v[36:37], v[6:7]
	v_pk_fma_f32 v[8:9], v[154:155], v[38:39], v[8:9]
	v_pk_fma_f32 v[10:11], v[156:157], v[40:41], v[10:11]
	v_cvt_f32_f16_e32 v26, v98
	v_cvt_f32_f16_sdwa v27, v98 dst_sel:DWORD dst_unused:UNUSED_PAD src0_sel:WORD_1
	v_cvt_f32_f16_e32 v28, v99
	v_cvt_f32_f16_sdwa v29, v99 dst_sel:DWORD dst_unused:UNUSED_PAD src0_sel:WORD_1
	v_cvt_f32_f16_e32 v30, v100
	v_cvt_f32_f16_sdwa v31, v100 dst_sel:DWORD dst_unused:UNUSED_PAD src0_sel:WORD_1
	v_cvt_f32_f16_e32 v32, v101
	v_cvt_f32_f16_sdwa v33, v101 dst_sel:DWORD dst_unused:UNUSED_PAD src0_sel:WORD_1
	v_cvt_f32_f16_e32 v34, v102
	v_cvt_f32_f16_sdwa v35, v102 dst_sel:DWORD dst_unused:UNUSED_PAD src0_sel:WORD_1
	v_cvt_f32_f16_e32 v36, v103
	v_cvt_f32_f16_sdwa v37, v103 dst_sel:DWORD dst_unused:UNUSED_PAD src0_sel:WORD_1
	v_cvt_f32_f16_e32 v38, v104
	v_cvt_f32_f16_sdwa v39, v104 dst_sel:DWORD dst_unused:UNUSED_PAD src0_sel:WORD_1
	v_cvt_f32_f16_e32 v40, v105
	v_cvt_f32_f16_sdwa v41, v105 dst_sel:DWORD dst_unused:UNUSED_PAD src0_sel:WORD_1
	v_pk_fma_f32 v[12:13], v[158:159], v[26:27], v[12:13]
	v_pk_fma_f32 v[14:15], v[160:161], v[28:29], v[14:15]
	v_pk_fma_f32 v[16:17], v[162:163], v[30:31], v[16:17]
	v_pk_fma_f32 v[18:19], v[164:165], v[32:33], v[18:19]
	v_pk_fma_f32 v[4:5], v[166:167], v[34:35], v[4:5]
	v_pk_fma_f32 v[6:7], v[168:169], v[36:37], v[6:7]
	v_pk_fma_f32 v[8:9], v[170:171], v[38:39], v[8:9]
	v_pk_fma_f32 v[10:11], v[172:173], v[40:41], v[10:11]

.LBB0_1099:
	s_and_b64 vcc, exec, s[24:25]
	s_cbranch_vccz .LBB0_1115
	s_ashr_i32 s36, s34, 3
	v_mov_b32_e32 v68, v200
	s_lshl_b32 s31, s36, 6
	s_lshl_b32 s24, s34, 3
	s_and_b32 s28, s34, 7
	s_and_b32 s24, s24, 0xffffff00
	s_and_b32 s25, s31, 0xfffff000
	s_load_dwordx2 s[26:27], s[22:23], 0xa0
	s_cmp_lt_i32 s36, 64
	v_lshlrev_b32_e32 v24, 4, v68
	s_cselect_b32 s30, 0x100, s38
	s_cselect_b32 s29, s24, s25
	v_and_b32_e32 v22, 48, v24
	s_lshl_b32 s37, s28, 6
	v_or_b32_e32 v2, s37, v22
	v_lshlrev_b32_e32 v0, 2, v2
	s_load_dwordx2 s[24:25], s[22:23], 0x110
	s_waitcnt lgkmcnt(0)
	global_load_dwordx4 v[8:11], v0, s[26:27] offset:48
	global_load_dwordx4 v[4:7], v0, s[26:27] offset:32
	global_load_dwordx4 v[16:19], v0, s[26:27] offset:16
	global_load_dwordx4 v[12:15], v0, s[26:27]
	v_bfe_u32 v23, v68, 2, 6
	v_or_b32_e32 v25, s31, v23
	s_add_i32 s30, s29, s30
	v_add_u32_e32 v1, -2, v25
	v_lshlrev_b32_e32 v2, 1, v2
	v_lshl_add_u64 v[20:21], s[24:25], 0, v[2:3]
	s_mov_b64 s[26:27], 0xaa08000
	v_cmp_le_i32_e32 vcc, s29, v1
	v_cmp_gt_i32_e64 s[42:43], s30, v1
	v_lshl_add_u64 v[20:21], v[20:21], 0, s[26:27]
	s_load_dwordx2 s[42:43], s[22:23], 0x98
	v_mov_b32_e32 v74, 0
	v_mov_b32_e32 v75, 0
	v_mov_b32_e32 v76, 0
	v_mov_b32_e32 v77, 0
	v_mov_b32_e32 v78, 0
	v_mov_b32_e32 v79, 0
	v_mov_b32_e32 v80, 0
	v_mov_b32_e32 v81, 0
	v_mov_b32_e32 v82, 0
	v_mov_b32_e32 v83, 0
	v_mov_b32_e32 v84, 0
	v_mov_b32_e32 v85, 0
	v_mov_b32_e32 v86, 0
	v_mov_b32_e32 v87, 0
	v_mov_b32_e32 v88, 0
	v_mov_b32_e32 v89, 0
	v_mov_b32_e32 v90, 0
	v_mov_b32_e32 v91, 0
	v_mov_b32_e32 v92, 0
	v_mov_b32_e32 v93, 0
	v_mov_b32_e32 v94, 0
	v_mov_b32_e32 v95, 0
	v_mov_b32_e32 v96, 0
	v_mov_b32_e32 v97, 0
	v_mov_b32_e32 v98, 0
	v_mov_b32_e32 v99, 0
	v_mov_b32_e32 v100, 0
	v_mov_b32_e32 v101, 0
	v_mov_b32_e32 v102, 0
	v_mov_b32_e32 v103, 0
	v_mov_b32_e32 v104, 0
	v_mov_b32_e32 v105, 0
	v_add_u32_e32 v108, 0x1000, v0
	v_add_u32_e32 v109, -2, v25
	v_cmp_le_i32_e32 vcc, s29, v109
	v_cmp_gt_i32_e64 s[26:27], s30, v109
	s_and_b64 vcc, vcc, s[26:27]
	s_and_saveexec_b64 s[26:27], vcc
	s_cbranch_execz .Lcva_0
	v_mad_i64_i32 v[106:107], vcc, v109, s97, v[20:21]
	global_load_dwordx4 v[74:77], v[106:107], off
	global_load_dwordx4 v[78:81], v[106:107], off offset:16
.Lcva_0:
	s_or_b64 exec, exec, s[26:27]
	v_add_u32_e32 v109, -1, v25
	v_cmp_le_i32_e32 vcc, s29, v109
	v_cmp_gt_i32_e64 s[26:27], s30, v109
	s_and_b64 vcc, vcc, s[26:27]
	s_and_saveexec_b64 s[26:27], vcc
	s_cbranch_execz .Lcva_1
	v_mad_i64_i32 v[106:107], vcc, v109, s97, v[20:21]
	global_load_dwordx4 v[82:85], v[106:107], off
	global_load_dwordx4 v[86:89], v[106:107], off offset:16
.Lcva_1:
	s_or_b64 exec, exec, s[26:27]
	v_mov_b32_e32 v109, v25
	v_cmp_le_i32_e32 vcc, s29, v109
	v_cmp_gt_i32_e64 s[26:27], s30, v109
	s_and_b64 vcc, vcc, s[26:27]
	s_and_saveexec_b64 s[26:27], vcc
	s_cbranch_execz .Lcva_2
	v_mad_i64_i32 v[106:107], vcc, v109, s97, v[20:21]
	global_load_dwordx4 v[90:93], v[106:107], off
	global_load_dwordx4 v[94:97], v[106:107], off offset:16
.Lcva_2:
	s_or_b64 exec, exec, s[26:27]
	v_add_u32_e32 v109, 1, v25
	v_cmp_le_i32_e32 vcc, s29, v109
	v_cmp_gt_i32_e64 s[26:27], s30, v109
	s_and_b64 vcc, vcc, s[26:27]
	s_and_saveexec_b64 s[26:27], vcc
	s_cbranch_execz .Lcva_3
	v_mad_i64_i32 v[106:107], vcc, v109, s97, v[20:21]
	global_load_dwordx4 v[98:101], v[106:107], off
	global_load_dwordx4 v[102:105], v[106:107], off offset:16
.Lcva_3:
	s_or_b64 exec, exec, s[26:27]
	s_waitcnt lgkmcnt(0)
	global_load_dwordx4 v[110:113], v0, s[42:43]
	global_load_dwordx4 v[114:117], v0, s[42:43] offset:16
	global_load_dwordx4 v[118:121], v0, s[42:43] offset:32
	global_load_dwordx4 v[122:125], v0, s[42:43] offset:48
	global_load_dwordx4 v[126:129], v0, s[42:43] offset:2048
	global_load_dwordx4 v[130:133], v0, s[42:43] offset:2064
	global_load_dwordx4 v[134:137], v0, s[42:43] offset:2080
	global_load_dwordx4 v[138:141], v0, s[42:43] offset:2096
	global_load_dwordx4 v[142:145], v108, s[42:43]
	global_load_dwordx4 v[146:149], v108, s[42:43] offset:16
	global_load_dwordx4 v[150:153], v108, s[42:43] offset:32
	global_load_dwordx4 v[154:157], v108, s[42:43] offset:48
	global_load_dwordx4 v[158:161], v108, s[42:43] offset:2048
	global_load_dwordx4 v[162:165], v108, s[42:43] offset:2064
	global_load_dwordx4 v[166:169], v108, s[42:43] offset:2080
	global_load_dwordx4 v[170:173], v108, s[42:43] offset:2096
	s_waitcnt vmcnt(0)
	v_cvt_f32_f16_e32 v26, v74
	v_cvt_f32_f16_sdwa v27, v74 dst_sel:DWORD dst_unused:UNUSED_PAD src0_sel:WORD_1
	v_cvt_f32_f16_e32 v28, v75
	v_cvt_f32_f16_sdwa v29, v75 dst_sel:DWORD dst_unused:UNUSED_PAD src0_sel:WORD_1
	v_cvt_f32_f16_e32 v30, v76
	v_cvt_f32_f16_sdwa v31, v76 dst_sel:DWORD dst_unused:UNUSED_PAD src0_sel:WORD_1
	v_cvt_f32_f16_e32 v32, v77
	v_cvt_f32_f16_sdwa v33, v77 dst_sel:DWORD dst_unused:UNUSED_PAD src0_sel:WORD_1
	v_cvt_f32_f16_e32 v34, v78
	v_cvt_f32_f16_sdwa v35, v78 dst_sel:DWORD dst_unused:UNUSED_PAD src0_sel:WORD_1
	v_cvt_f32_f16_e32 v36, v79
	v_cvt_f32_f16_sdwa v37, v79 dst_sel:DWORD dst_unused:UNUSED_PAD src0_sel:WORD_1
	v_cvt_f32_f16_e32 v38, v80
	v_cvt_f32_f16_sdwa v39, v80 dst_sel:DWORD dst_unused:UNUSED_PAD src0_sel:WORD_1
	v_cvt_f32_f16_e32 v40, v81
	v_cvt_f32_f16_sdwa v41, v81 dst_sel:DWORD dst_unused:UNUSED_PAD src0_sel:WORD_1
	v_pk_fma_f32 v[12:13], v[110:111], v[26:27], v[12:13]
	v_pk_fma_f32 v[14:15], v[112:113], v[28:29], v[14:15]
	v_pk_fma_f32 v[16:17], v[114:115], v[30:31], v[16:17]
	v_pk_fma_f32 v[18:19], v[116:117], v[32:33], v[18:19]
	v_pk_fma_f32 v[4:5], v[118:119], v[34:35], v[4:5]
	v_pk_fma_f32 v[6:7], v[120:121], v[36:37], v[6:7]
	v_pk_fma_f32 v[8:9], v[122:123], v[38:39], v[8:9]
	v_pk_fma_f32 v[10:11], v[124:125], v[40:41], v[10:11]
	v_cvt_f32_f16_e32 v26, v82
	v_cvt_f32_f16_sdwa v27, v82 dst_sel:DWORD dst_unused:UNUSED_PAD src0_sel:WORD_1
	v_cvt_f32_f16_e32 v28, v83
	v_cvt_f32_f16_sdwa v29, v83 dst_sel:DWORD dst_unused:UNUSED_PAD src0_sel:WORD_1
	v_cvt_f32_f16_e32 v30, v84
	v_cvt_f32_f16_sdwa v31, v84 dst_sel:DWORD dst_unused:UNUSED_PAD src0_sel:WORD_1
	v_cvt_f32_f16_e32 v32, v85
	v_cvt_f32_f16_sdwa v33, v85 dst_sel:DWORD dst_unused:UNUSED_PAD src0_sel:WORD_1
	v_cvt_f32_f16_e32 v34, v86
	v_cvt_f32_f16_sdwa v35, v86 dst_sel:DWORD dst_unused:UNUSED_PAD src0_sel:WORD_1
	v_cvt_f32_f16_e32 v36, v87
	v_cvt_f32_f16_sdwa v37, v87 dst_sel:DWORD dst_unused:UNUSED_PAD src0_sel:WORD_1
	v_cvt_f32_f16_e32 v38, v88
	v_cvt_f32_f16_sdwa v39, v88 dst_sel:DWORD dst_unused:UNUSED_PAD src0_sel:WORD_1
	v_cvt_f32_f16_e32 v40, v89
	v_cvt_f32_f16_sdwa v41, v89 dst_sel:DWORD dst_unused:UNUSED_PAD src0_sel:WORD_1
	v_pk_fma_f32 v[12:13], v[126:127], v[26:27], v[12:13]
	v_pk_fma_f32 v[14:15], v[128:129], v[28:29], v[14:15]
	v_pk_fma_f32 v[16:17], v[130:131], v[30:31], v[16:17]
	v_pk_fma_f32 v[18:19], v[132:133], v[32:33], v[18:19]
	v_pk_fma_f32 v[4:5], v[134:135], v[34:35], v[4:5]
	v_pk_fma_f32 v[6:7], v[136:137], v[36:37], v[6:7]
	v_pk_fma_f32 v[8:9], v[138:139], v[38:39], v[8:9]
	v_pk_fma_f32 v[10:11], v[140:141], v[40:41], v[10:11]
	v_cvt_f32_f16_e32 v26, v90
	v_cvt_f32_f16_sdwa v27, v90 dst_sel:DWORD dst_unused:UNUSED_PAD src0_sel:WORD_1
	v_cvt_f32_f16_e32 v28, v91
	v_cvt_f32_f16_sdwa v29, v91 dst_sel:DWORD dst_unused:UNUSED_PAD src0_sel:WORD_1
	v_cvt_f32_f16_e32 v30, v92
	v_cvt_f32_f16_sdwa v31, v92 dst_sel:DWORD dst_unused:UNUSED_PAD src0_sel:WORD_1
	v_cvt_f32_f16_e32 v32, v93
	v_cvt_f32_f16_sdwa v33, v93 dst_sel:DWORD dst_unused:UNUSED_PAD src0_sel:WORD_1
	v_cvt_f32_f16_e32 v34, v94
	v_cvt_f32_f16_sdwa v35, v94 dst_sel:DWORD dst_unused:UNUSED_PAD src0_sel:WORD_1
	v_cvt_f32_f16_e32 v36, v95
	v_cvt_f32_f16_sdwa v37, v95 dst_sel:DWORD dst_unused:UNUSED_PAD src0_sel:WORD_1
	v_cvt_f32_f16_e32 v38, v96
	v_cvt_f32_f16_sdwa v39, v96 dst_sel:DWORD dst_unused:UNUSED_PAD src0_sel:WORD_1
	v_cvt_f32_f16_e32 v40, v97
	v_cvt_f32_f16_sdwa v41, v97 dst_sel:DWORD dst_unused:UNUSED_PAD src0_sel:WORD_1
	v_pk_fma_f32 v[12:13], v[142:143], v[26:27], v[12:13]
	v_pk_fma_f32 v[14:15], v[144:145], v[28:29], v[14:15]
	v_pk_fma_f32 v[16:17], v[146:147], v[30:31], v[16:17]
	v_pk_fma_f32 v[18:19], v[148:149], v[32:33], v[18:19]
	v_pk_fma_f32 v[4:5], v[150:151], v[34:35], v[4:5]
	v_pk_fma_f32 v[6:7], v[152:153], v[36:37], v[6:7]
	v_pk_fma_f32 v[8:9], v[154:155], v[38:39], v[8:9]
	v_pk_fma_f32 v[10:11], v[156:157], v[40:41], v[10:11]
	v_cvt_f32_f16_e32 v26, v98
	v_cvt_f32_f16_sdwa v27, v98 dst_sel:DWORD dst_unused:UNUSED_PAD src0_sel:WORD_1
	v_cvt_f32_f16_e32 v28, v99
	v_cvt_f32_f16_sdwa v29, v99 dst_sel:DWORD dst_unused:UNUSED_PAD src0_sel:WORD_1
	v_cvt_f32_f16_e32 v30, v100
	v_cvt_f32_f16_sdwa v31, v100 dst_sel:DWORD dst_unused:UNUSED_PAD src0_sel:WORD_1
	v_cvt_f32_f16_e32 v32, v101
	v_cvt_f32_f16_sdwa v33, v101 dst_sel:DWORD dst_unused:UNUSED_PAD src0_sel:WORD_1
	v_cvt_f32_f16_e32 v34, v102
	v_cvt_f32_f16_sdwa v35, v102 dst_sel:DWORD dst_unused:UNUSED_PAD src0_sel:WORD_1
	v_cvt_f32_f16_e32 v36, v103
	v_cvt_f32_f16_sdwa v37, v103 dst_sel:DWORD dst_unused:UNUSED_PAD src0_sel:WORD_1
	v_cvt_f32_f16_e32 v38, v104
	v_cvt_f32_f16_sdwa v39, v104 dst_sel:DWORD dst_unused:UNUSED_PAD src0_sel:WORD_1
	v_cvt_f32_f16_e32 v40, v105
	v_cvt_f32_f16_sdwa v41, v105 dst_sel:DWORD dst_unused:UNUSED_PAD src0_sel:WORD_1
	v_pk_fma_f32 v[12:13], v[158:159], v[26:27], v[12:13]
	v_pk_fma_f32 v[14:15], v[160:161], v[28:29], v[14:15]
	v_pk_fma_f32 v[16:17], v[162:163], v[30:31], v[16:17]
	v_pk_fma_f32 v[18:19], v[164:165], v[32:33], v[18:19]
	v_pk_fma_f32 v[4:5], v[166:167], v[34:35], v[4:5]
	v_pk_fma_f32 v[6:7], v[168:169], v[36:37], v[6:7]
	v_pk_fma_f32 v[8:9], v[170:171], v[38:39], v[8:9]
	v_pk_fma_f32 v[10:11], v[172:173], v[40:41], v[10:11]
